# grid barrier: non-leader workgroups poll the cross-XCC release generation directly (one fewer release hop per barrier)
# speedup vs baseline: 1.0054x; 1.0054x over previous
.LBB0_127:
	s_or_b64 exec, exec, s[20:21]
	v_cvt_f32_u32_e32 v5, v3
	s_waitcnt vmcnt(0)
	v_readfirstlane_b32 s3, v4
	v_sub_u32_e32 v4, 0, v3
	v_rcp_iflag_f32_e32 v5, v5
	v_add_u32_e32 v6, s3, v2
	v_mul_f32_e32 v5, 0x4f7ffffe, v5
	v_cvt_u32_f32_e32 v5, v5
	v_mul_lo_u32 v2, v4, v5
	v_mul_hi_u32 v2, v5, v2
	v_add_u32_e32 v2, v5, v2
	v_mul_hi_u32 v2, v6, v2
	v_mul_lo_u32 v4, v2, v3
	v_sub_u32_e32 v4, v6, v4
	v_add_u32_e32 v5, 1, v2
	v_cmp_ge_u32_e32 vcc, v4, v3
	s_nop 1
	v_cndmask_b32_e32 v2, v2, v5, vcc
	v_sub_u32_e32 v5, v4, v3
	v_cndmask_b32_e32 v4, v4, v5, vcc
	v_add_u32_e32 v5, 1, v2
	v_cmp_ge_u32_e32 vcc, v4, v3
	v_add_u32_e32 v4, 1, v6
	s_nop 0
	v_cndmask_b32_e32 v2, v2, v5, vcc
	v_mul_lo_u32 v5, v3, v2
	v_add_u32_e32 v3, v5, v3
	v_cmp_ne_u32_e32 vcc, v4, v3
	s_and_saveexec_b64 s[4:5], vcc
	s_xor_b64 s[20:21], exec, s[4:5]
	s_cbranch_execz .LBB0_141
	s_waitcnt lgkmcnt(0)
	v_mov_b32_e32 v1, 0
	global_load_dword v3, v1, s[92:93] sc1
	s_waitcnt vmcnt(0)
	v_cmp_eq_u32_e32 vcc, v3, v2
	s_and_saveexec_b64 s[22:23], vcc
	s_cbranch_execz .LBB0_140
	s_mov_b32 s3, 1
	s_mov_b64 s[24:25], 0
	s_branch .LBB0_131

.LBB0_133:
	global_load_dword v3, v1, s[92:93] sc1
	s_add_i32 s3, s3, 1
	s_mov_b64 s[30:31], -1
	s_waitcnt vmcnt(0)
	v_cmp_ne_u32_e32 vcc, v3, v2
	s_orn2_b64 s[28:29], vcc, exec
	s_branch .LBB0_130

.LBB0_344:
	s_or_b64 exec, exec, s[20:21]
	v_cvt_f32_u32_e32 v5, v3
	s_waitcnt vmcnt(0)
	v_readfirstlane_b32 s4, v4
	v_sub_u32_e32 v4, 0, v3
	v_rcp_iflag_f32_e32 v5, v5
	v_add_u32_e32 v6, s4, v2
	v_mul_f32_e32 v5, 0x4f7ffffe, v5
	v_cvt_u32_f32_e32 v5, v5
	v_mul_lo_u32 v2, v4, v5
	v_mul_hi_u32 v2, v5, v2
	v_add_u32_e32 v2, v5, v2
	v_mul_hi_u32 v2, v6, v2
	v_mul_lo_u32 v4, v2, v3
	v_sub_u32_e32 v4, v6, v4
	v_add_u32_e32 v5, 1, v2
	v_cmp_ge_u32_e32 vcc, v4, v3
	s_nop 1
	v_cndmask_b32_e32 v2, v2, v5, vcc
	v_sub_u32_e32 v5, v4, v3
	v_cndmask_b32_e32 v4, v4, v5, vcc
	v_add_u32_e32 v5, 1, v2
	v_cmp_ge_u32_e32 vcc, v4, v3
	v_add_u32_e32 v4, 1, v6
	s_nop 0
	v_cndmask_b32_e32 v2, v2, v5, vcc
	v_mul_lo_u32 v5, v3, v2
	v_add_u32_e32 v3, v5, v3
	v_cmp_ne_u32_e32 vcc, v4, v3
	s_and_saveexec_b64 s[4:5], vcc
	s_xor_b64 s[20:21], exec, s[4:5]
	s_cbranch_execz .LBB0_358
	s_waitcnt lgkmcnt(0)
	v_mov_b32_e32 v1, 0
	global_load_dword v3, v1, s[92:93] sc1
	s_waitcnt vmcnt(0)
	v_cmp_eq_u32_e32 vcc, v3, v2
	s_and_saveexec_b64 s[22:23], vcc
	s_cbranch_execz .LBB0_357
	s_mov_b32 s4, 1
	s_mov_b64 s[24:25], 0
	s_branch .LBB0_348

.LBB0_350:
	global_load_dword v3, v1, s[92:93] sc1
	s_add_i32 s4, s4, 1
	s_mov_b64 s[30:31], -1
	s_waitcnt vmcnt(0)
	v_cmp_ne_u32_e32 vcc, v3, v2
	s_orn2_b64 s[28:29], vcc, exec
	s_branch .LBB0_347

.LBB0_614:
	s_or_b64 exec, exec, s[20:21]
	v_cvt_f32_u32_e32 v6, v4
	s_waitcnt vmcnt(0)
	v_readfirstlane_b32 s4, v5
	v_sub_u32_e32 v5, 0, v4
	v_rcp_iflag_f32_e32 v6, v6
	v_add_u32_e32 v7, s4, v3
	v_mul_f32_e32 v6, 0x4f7ffffe, v6
	v_cvt_u32_f32_e32 v6, v6
	v_mul_lo_u32 v3, v5, v6
	v_mul_hi_u32 v3, v6, v3
	v_add_u32_e32 v3, v6, v3
	v_mul_hi_u32 v3, v7, v3
	v_mul_lo_u32 v5, v3, v4
	v_sub_u32_e32 v5, v7, v5
	v_add_u32_e32 v6, 1, v3
	v_cmp_ge_u32_e32 vcc, v5, v4
	s_nop 1
	v_cndmask_b32_e32 v3, v3, v6, vcc
	v_sub_u32_e32 v6, v5, v4
	v_cndmask_b32_e32 v5, v5, v6, vcc
	v_add_u32_e32 v6, 1, v3
	v_cmp_ge_u32_e32 vcc, v5, v4
	v_add_u32_e32 v5, 1, v7
	s_nop 0
	v_cndmask_b32_e32 v3, v3, v6, vcc
	v_mul_lo_u32 v6, v4, v3
	v_add_u32_e32 v4, v6, v4
	v_cmp_ne_u32_e32 vcc, v5, v4
	s_and_saveexec_b64 s[4:5], vcc
	s_xor_b64 s[20:21], exec, s[4:5]
	s_cbranch_execz .LBB0_628
	s_waitcnt lgkmcnt(0)
	v_mov_b32_e32 v2, 0
	global_load_dword v4, v2, s[92:93] sc1
	s_waitcnt vmcnt(0)
	v_cmp_eq_u32_e32 vcc, v4, v3
	s_and_saveexec_b64 s[22:23], vcc
	s_cbranch_execz .LBB0_627
	s_mov_b32 s4, 1
	s_mov_b64 s[24:25], 0
	s_branch .LBB0_618

.LBB0_620:
	global_load_dword v4, v2, s[92:93] sc1
	s_add_i32 s4, s4, 1
	s_mov_b64 s[30:31], -1
	s_waitcnt vmcnt(0)
	v_cmp_ne_u32_e32 vcc, v4, v3
	s_orn2_b64 s[28:29], vcc, exec
	s_branch .LBB0_617

.LBB0_1559:
	s_or_b64 exec, exec, s[18:19]
	v_cvt_f32_u32_e32 v6, v4
	s_waitcnt vmcnt(0)
	v_readfirstlane_b32 s4, v5
	v_sub_u32_e32 v5, 0, v4
	v_rcp_iflag_f32_e32 v6, v6
	v_add_u32_e32 v7, s4, v3
	v_mul_f32_e32 v6, 0x4f7ffffe, v6
	v_cvt_u32_f32_e32 v6, v6
	v_mul_lo_u32 v3, v5, v6
	v_mul_hi_u32 v3, v6, v3
	v_add_u32_e32 v3, v6, v3
	v_mul_hi_u32 v3, v7, v3
	v_mul_lo_u32 v5, v3, v4
	v_sub_u32_e32 v5, v7, v5
	v_add_u32_e32 v6, 1, v3
	v_cmp_ge_u32_e32 vcc, v5, v4
	s_nop 1
	v_cndmask_b32_e32 v3, v3, v6, vcc
	v_sub_u32_e32 v6, v5, v4
	v_cndmask_b32_e32 v5, v5, v6, vcc
	v_add_u32_e32 v6, 1, v3
	v_cmp_ge_u32_e32 vcc, v5, v4
	v_add_u32_e32 v5, 1, v7
	s_nop 0
	v_cndmask_b32_e32 v3, v3, v6, vcc
	v_mul_lo_u32 v6, v4, v3
	v_add_u32_e32 v4, v6, v4
	v_cmp_ne_u32_e32 vcc, v5, v4
	s_and_saveexec_b64 s[4:5], vcc
	s_xor_b64 s[18:19], exec, s[4:5]
	s_cbranch_execz .LBB0_1573
	s_waitcnt lgkmcnt(0)
	v_mov_b32_e32 v2, 0
	global_load_dword v4, v2, s[92:93] sc1
	s_waitcnt vmcnt(0)
	v_cmp_eq_u32_e32 vcc, v4, v3
	s_and_saveexec_b64 s[20:21], vcc
	s_cbranch_execz .LBB0_1572
	s_mov_b32 s4, 1
	s_mov_b64 s[22:23], 0
	s_branch .LBB0_1563

.LBB0_1565:
	global_load_dword v4, v2, s[92:93] sc1
	s_add_i32 s4, s4, 1
	s_mov_b64 s[28:29], -1
	s_waitcnt vmcnt(0)
	v_cmp_ne_u32_e32 vcc, v4, v3
	s_orn2_b64 s[26:27], vcc, exec
	s_branch .LBB0_1562

.LBB0_1646:
	s_or_b64 exec, exec, s[4:5]
	v_cvt_f32_u32_e32 v5, v3
	s_waitcnt vmcnt(0)
	v_readfirstlane_b32 s4, v4
	v_sub_u32_e32 v4, 0, v3
	v_rcp_iflag_f32_e32 v5, v5
	v_add_u32_e32 v6, s4, v2
	v_mul_f32_e32 v5, 0x4f7ffffe, v5
	v_cvt_u32_f32_e32 v5, v5
	v_mul_lo_u32 v2, v4, v5
	v_mul_hi_u32 v2, v5, v2
	v_add_u32_e32 v2, v5, v2
	v_mul_hi_u32 v2, v6, v2
	v_mul_lo_u32 v4, v2, v3
	v_sub_u32_e32 v4, v6, v4
	v_add_u32_e32 v5, 1, v2
	v_cmp_ge_u32_e32 vcc, v4, v3
	s_nop 1
	v_cndmask_b32_e32 v2, v2, v5, vcc
	v_sub_u32_e32 v5, v4, v3
	v_cndmask_b32_e32 v4, v4, v5, vcc
	v_add_u32_e32 v5, 1, v2
	v_cmp_ge_u32_e32 vcc, v4, v3
	v_add_u32_e32 v4, 1, v6
	s_nop 0
	v_cndmask_b32_e32 v2, v2, v5, vcc
	v_mul_lo_u32 v5, v3, v2
	v_add_u32_e32 v3, v5, v3
	v_cmp_ne_u32_e32 vcc, v4, v3
	s_and_saveexec_b64 s[4:5], vcc
	s_xor_b64 s[4:5], exec, s[4:5]
	s_cbranch_execz .LBB0_1660
	s_waitcnt lgkmcnt(0)
	v_mov_b32_e32 v1, 0
	global_load_dword v3, v1, s[92:93] sc1
	s_waitcnt vmcnt(0)
	v_cmp_eq_u32_e32 vcc, v3, v2
	s_and_saveexec_b64 s[6:7], vcc
	s_cbranch_execz .LBB0_1659
	s_mov_b32 s18, 1
	s_mov_b64 s[8:9], 0
	s_branch .LBB0_1650

.LBB0_1652:
	global_load_dword v3, v1, s[92:93] sc1
	s_add_i32 s18, s18, 1
	s_mov_b64 s[14:15], -1
	s_waitcnt vmcnt(0)
	v_cmp_ne_u32_e32 vcc, v3, v2
	s_orn2_b64 s[12:13], vcc, exec
	s_branch .LBB0_1649
